# attention QK^T MFMAs re-ordered (no back-to-back dependent pairs) + counted vmcnt ladder for the key tiles
# baseline (speedup 1.0000x reference)
; __device__ __forceinline__ void attn_unit(LAS unsigned char* lds, int b, int h, int blk, const bf16_t* Q, const bf16_t* Kb, const bf16_t* Vt1, const bf16_t* Vt4, const bf16_t* Vt16,
;                                           bf16_t* MIX, i64* ssq_a, int wid, int lane_in) {
;     ...
;             int qtok[2]; bf16x8 qf[2][2];
; #pragma unroll
;             for (int g = 0; g < 2; ++g) { qtok[g] = ((n0 + 16 * g + qi) << lg) + r; const bf16_t* qp = Q + bhb + (size_t)qtok[g] * 64 + kq * 16; qf[g][0] = *(const bf16x8*)qp; qf[g][1] = *(const bf16x8*)(qp + 8); }
;             bf16x8 kf[10][2];
; #pragma unroll
;             for (int t = 0; t < 10; ++t) {
;                 const int widx = 32 * (t >> 1) + 8 * (qi >> 2) + 4 * (t & 1) + (qi & 3);
;                 int kn = ws_ + widx; kn = kn < 0 ? 0 : (kn > L - 1 ? L - 1 : kn);
;                 const bf16_t* kp = Kb + bhb + (size_t)((kn << lg) + r) * 64 + kq * 16;
;                 kf[t][0] = *(const bf16x8*)kp; kf[t][1] = *(const bf16x8*)(kp + 8);
;             }
;             __builtin_amdgcn_sched_barrier(0);
;             f32x4 s[2][10];
; #pragma unroll
;             for (int t = 0; t < 10; ++t)
; #pragma unroll
;                 for (int g = 0; g < 2; ++g) {
;                     f32x4 z = (f32x4){0.f, 0.f, 0.f, 0.f};
;                     z = __builtin_amdgcn_mfma_f32_16x16x32_bf16(kf[t][0], qf[g][0], z, 0, 0, 0);
;                     z = __builtin_amdgcn_mfma_f32_16x16x32_bf16(kf[t][1], qf[g][1], z, 0, 0, 0);
;                     s[g][t] = z;
;                 }
.LBB0_1090:
	v_add_u32_e32 v0, s5, v138
	v_lshlrev_b32_e32 v2, s31, v0
	v_add_lshl_u32 v0, v0, 16, s31
	s_sub_i32 s22, s5, 64
	v_add_u32_e32 v130, s4, v0
	v_add_u32_e32 v0, s22, v139
	v_min_i32_e32 v18, s78, v0
	v_cmp_lt_i32_e32 vcc, -1, v0
	v_add_u32_e32 v132, s4, v2
	v_ashrrev_i32_e32 v133, 31, v132
	v_cndmask_b32_e32 v0, 0, v18, vcc
	v_lshlrev_b32_e32 v0, s31, v0
	v_add_u32_e32 v18, s4, v0
	v_add_u32_e32 v0, s22, v144
	v_min_i32_e32 v26, s78, v0
	v_cmp_lt_i32_e32 vcc, -1, v0
	v_ashrrev_i32_e32 v131, 31, v130
	v_ashrrev_i32_e32 v19, 31, v18
	v_cndmask_b32_e32 v0, 0, v26, vcc
	v_lshlrev_b32_e32 v0, s31, v0
	v_add_u32_e32 v26, s4, v0
	v_add_u32_e32 v0, s22, v145
	v_min_i32_e32 v34, s78, v0
	v_cmp_lt_i32_e32 vcc, -1, v0
	v_ashrrev_i32_e32 v27, 31, v26
	v_lshlrev_b64 v[2:3], 7, v[132:133]
	v_cndmask_b32_e32 v0, 0, v34, vcc
	v_lshlrev_b32_e32 v0, s31, v0
	v_add_u32_e32 v34, s4, v0
	v_add_u32_e32 v0, s22, v146
	v_min_i32_e32 v42, s78, v0
	v_cmp_lt_i32_e32 vcc, -1, v0
	v_ashrrev_i32_e32 v35, 31, v34
	v_lshlrev_b64 v[10:11], 7, v[130:131]
	v_cndmask_b32_e32 v0, 0, v42, vcc
	v_lshlrev_b32_e32 v0, s31, v0
	v_add_u32_e32 v42, s4, v0
	v_add_u32_e32 v0, s22, v147
	v_min_i32_e32 v0, s78, v0
	v_lshlrev_b32_e32 v0, s31, v0
	v_add_u32_e32 v0, s4, v0
	v_lshlrev_b64 v[50:51], 7, v[0:1]
	v_add_u32_e32 v0, s22, v148
	v_min_i32_e32 v0, s78, v0
	v_lshlrev_b32_e32 v0, s31, v0
	v_add_u32_e32 v0, s4, v0
	v_lshlrev_b64 v[58:59], 7, v[0:1]
	v_add_u32_e32 v0, s22, v149
	v_min_i32_e32 v0, s78, v0
	v_lshlrev_b32_e32 v0, s31, v0
	v_add_u32_e32 v0, s4, v0
	v_lshlrev_b64 v[66:67], 7, v[0:1]
	v_add_u32_e32 v0, s22, v150
	v_min_i32_e32 v0, s78, v0
	v_lshlrev_b32_e32 v0, s31, v0
	v_add_u32_e32 v0, s4, v0
	v_lshlrev_b64 v[74:75], 7, v[0:1]
	v_add_u32_e32 v0, s22, v151
	v_min_i32_e32 v0, s78, v0
	v_lshlrev_b32_e32 v0, s31, v0
	v_add_u32_e32 v0, s4, v0
	v_lshlrev_b64 v[82:83], 7, v[0:1]
	v_add_u32_e32 v0, s22, v152
	v_min_i32_e32 v0, s78, v0
	v_lshlrev_b32_e32 v0, s31, v0
	v_ashrrev_i32_e32 v43, 31, v42
	v_add_u32_e32 v0, s4, v0
	v_lshlrev_b64 v[18:19], 7, v[18:19]
	v_lshlrev_b64 v[26:27], 7, v[26:27]
	v_lshlrev_b64 v[34:35], 7, v[34:35]
	v_lshlrev_b64 v[42:43], 7, v[42:43]
	v_lshlrev_b64 v[90:91], 7, v[0:1]
	v_lshl_add_u64 v[6:7], v[122:123], 0, v[2:3]
	v_lshl_add_u64 v[14:15], v[122:123], 0, v[10:11]
	v_lshl_add_u64 v[22:23], v[124:125], 0, v[18:19]
	v_lshl_add_u64 v[30:31], v[124:125], 0, v[26:27]
	v_lshl_add_u64 v[38:39], v[124:125], 0, v[34:35]
	v_lshl_add_u64 v[46:47], v[124:125], 0, v[42:43]
	v_lshl_add_u64 v[54:55], v[124:125], 0, v[50:51]
	v_lshl_add_u64 v[62:63], v[124:125], 0, v[58:59]
	v_lshl_add_u64 v[70:71], v[124:125], 0, v[66:67]
	v_lshl_add_u64 v[78:79], v[124:125], 0, v[74:75]
	v_lshl_add_u64 v[86:87], v[124:125], 0, v[82:83]
	v_lshl_add_u64 v[90:91], v[124:125], 0, v[90:91]
	global_load_dwordx4 v[2:5], v[6:7], off
	s_nop 0
	global_load_dwordx4 v[6:9], v[6:7], off offset:16
	s_nop 0
	global_load_dwordx4 v[10:13], v[14:15], off
	s_nop 0
	global_load_dwordx4 v[14:17], v[14:15], off offset:16
	s_nop 0
	global_load_dwordx4 v[18:21], v[22:23], off
	s_nop 0
	global_load_dwordx4 v[22:25], v[22:23], off offset:16
	s_nop 0
	global_load_dwordx4 v[26:29], v[30:31], off
	s_nop 0
	global_load_dwordx4 v[30:33], v[30:31], off offset:16
	s_nop 0
	global_load_dwordx4 v[34:37], v[38:39], off
	s_nop 0
	global_load_dwordx4 v[38:41], v[38:39], off offset:16
	s_nop 0
	global_load_dwordx4 v[42:45], v[46:47], off
	s_nop 0
	global_load_dwordx4 v[46:49], v[46:47], off offset:16
	s_nop 0
	global_load_dwordx4 v[50:53], v[54:55], off
	s_nop 0
	global_load_dwordx4 v[54:57], v[54:55], off offset:16
	s_nop 0
	global_load_dwordx4 v[58:61], v[62:63], off
	s_nop 0
	global_load_dwordx4 v[62:65], v[62:63], off offset:16
	s_nop 0
	global_load_dwordx4 v[66:69], v[70:71], off
	s_nop 0
	global_load_dwordx4 v[70:73], v[70:71], off offset:16
	s_nop 0
	global_load_dwordx4 v[74:77], v[78:79], off
	s_nop 0
	global_load_dwordx4 v[78:81], v[78:79], off offset:16
	s_nop 0
	global_load_dwordx4 v[82:85], v[86:87], off
	s_nop 0
	global_load_dwordx4 v[86:89], v[86:87], off offset:16
	s_nop 0
	global_load_dwordx4 v[156:159], v[90:91], off
	global_load_dwordx4 v[160:163], v[90:91], off offset:16
	s_waitcnt vmcnt(16)
	v_mfma_f32_16x16x32_bf16 v[164:167], v[18:21], v[2:5], 0
	v_mfma_f32_16x16x32_bf16 v[118:121], v[18:21], v[10:13], 0
	v_mfma_f32_16x16x32_bf16 v[168:171], v[26:29], v[2:5], 0
	v_mfma_f32_16x16x32_bf16 v[114:117], v[26:29], v[10:13], 0
	v_mfma_f32_16x16x32_bf16 v[164:167], v[22:25], v[6:9], v[164:167]
	v_mfma_f32_16x16x32_bf16 v[118:121], v[22:25], v[14:17], v[118:121]
	v_mfma_f32_16x16x32_bf16 v[168:171], v[30:33], v[6:9], v[168:171]
	v_mfma_f32_16x16x32_bf16 v[114:117], v[30:33], v[14:17], v[114:117]
	s_waitcnt vmcnt(12)
	v_mfma_f32_16x16x32_bf16 v[172:175], v[34:37], v[2:5], 0
	v_mfma_f32_16x16x32_bf16 v[110:113], v[34:37], v[10:13], 0
	v_mfma_f32_16x16x32_bf16 v[176:179], v[42:45], v[2:5], 0
	v_mfma_f32_16x16x32_bf16 v[106:109], v[42:45], v[10:13], 0
	v_mfma_f32_16x16x32_bf16 v[172:175], v[38:41], v[6:9], v[172:175]
	v_mfma_f32_16x16x32_bf16 v[110:113], v[38:41], v[14:17], v[110:113]
	v_mfma_f32_16x16x32_bf16 v[176:179], v[46:49], v[6:9], v[176:179]
	v_mfma_f32_16x16x32_bf16 v[106:109], v[46:49], v[14:17], v[106:109]
	s_waitcnt vmcnt(8)
	v_mfma_f32_16x16x32_bf16 v[180:183], v[50:53], v[2:5], 0
	v_mfma_f32_16x16x32_bf16 v[102:105], v[50:53], v[10:13], 0
	v_mfma_f32_16x16x32_bf16 v[184:187], v[58:61], v[2:5], 0
	v_mfma_f32_16x16x32_bf16 v[98:101], v[58:61], v[10:13], 0
	v_mfma_f32_16x16x32_bf16 v[180:183], v[54:57], v[6:9], v[180:183]
	v_mfma_f32_16x16x32_bf16 v[102:105], v[54:57], v[14:17], v[102:105]
	v_mfma_f32_16x16x32_bf16 v[184:187], v[62:65], v[6:9], v[184:187]
	v_mfma_f32_16x16x32_bf16 v[98:101], v[62:65], v[14:17], v[98:101]
	s_waitcnt vmcnt(4)
; __device__ __forceinline__ void attn_unit(LAS unsigned char* lds, int b, int h, int blk, const bf16_t* Q, const bf16_t* Kb, const bf16_t* Vt1, const bf16_t* Vt4, const bf16_t* Vt16,
;                                           bf16_t* MIX, i64* ssq_a, int wid, int lane_in) {
;     ...
;             for (int t = 0; t < 10; ++t)
; #pragma unroll
;                 for (int g = 0; g < 2; ++g) {
;                     f32x4 z = (f32x4){0.f, 0.f, 0.f, 0.f};
;                     z = __builtin_amdgcn_mfma_f32_16x16x32_bf16(kf[t][0], qf[g][0], z, 0, 0, 0);
;                     z = __builtin_amdgcn_mfma_f32_16x16x32_bf16(kf[t][1], qf[g][1], z, 0, 0, 0);
;                     s[g][t] = z;
;                 }
;             __builtin_amdgcn_sched_barrier(0);
;             bf16x8 vf[5][4];
; #pragma unroll
;             for (int c = 0; c < 5; ++c) {
;                 int gk = ws_ + 32 * c + 8 * kq; gk = (gk < 0 || gk >= L) ? 0 : gk;
;                 const bf16_t* vp = Vt + bhb + ((size_t)(r * (L >> 3) + (gk >> 3)) * 64 + qi) * 8;
; #pragma unroll
;                 for (int dt = 0; dt < 4; ++dt) vf[c][dt] = *(const bf16x8*)(vp + dt * 128);
;             }
;             __builtin_amdgcn_sched_barrier(0);
;             float mx[2], lsum[2];
; #pragma unroll
;             for (int g = 0; g < 2; ++g) {
;                 float m_ = -1e30f;
;                 int lo = 16 * g + qi, hi = 128 + 16 * g + qi; lo = lo > -ws_ ? lo : -ws_; hi = hi < L - 1 - ws_ ? hi : L - 1 - ws_;
;                 const int lo8 = lo - 8 * kq; const unsigned span = (unsigned)(hi - lo);
; #pragma unroll
;                 for (int t = 0; t < 10; ++t)
; #pragma unroll
;                     for (int i = 0; i < 4; ++i) {
;                         const int c = 32 * (t >> 1) + 4 * (t & 1) + i;
;                         const bool ok = (unsigned)(c - lo8) <= span;
;                         const float v = ok ? s[g][t][i] : -1e30f; s[g][t][i] = v; m_ = fmaxf(m_, v);
	v_mfma_f32_16x16x32_bf16 v[188:191], v[66:69], v[2:5], 0
	v_mfma_f32_16x16x32_bf16 v[94:97], v[66:69], v[10:13], 0
	v_mfma_f32_16x16x32_bf16 v[192:195], v[74:77], v[2:5], 0
	v_mfma_f32_16x16x32_bf16 v[90:93], v[74:77], v[10:13], 0
	v_mfma_f32_16x16x32_bf16 v[188:191], v[70:73], v[6:9], v[188:191]
	v_mfma_f32_16x16x32_bf16 v[94:97], v[70:73], v[14:17], v[94:97]
	v_mfma_f32_16x16x32_bf16 v[192:195], v[78:81], v[6:9], v[192:195]
	v_mfma_f32_16x16x32_bf16 v[90:93], v[78:81], v[14:17], v[90:93]
	s_waitcnt vmcnt(0)
	v_mfma_f32_16x16x32_bf16 v[196:199], v[82:85], v[2:5], 0
	v_mfma_f32_16x16x32_bf16 v[18:21], v[82:85], v[10:13], 0
	v_mfma_f32_16x16x32_bf16 v[200:203], v[156:159], v[2:5], 0
	v_mfma_f32_16x16x32_bf16 v[22:25], v[156:159], v[10:13], 0
	v_mfma_f32_16x16x32_bf16 v[196:199], v[86:89], v[6:9], v[196:199]
	v_mfma_f32_16x16x32_bf16 v[86:89], v[86:89], v[14:17], v[18:21]
	v_mfma_f32_16x16x32_bf16 v[200:203], v[160:163], v[6:9], v[200:203]
	v_mfma_f32_16x16x32_bf16 v[82:85], v[160:163], v[14:17], v[22:25]
	v_add_u32_e32 v0, s22, v140
	v_cmp_gt_i32_e32 vcc, s54, v0
	v_cmp_lt_i32_e64 s[48:49], -1, v0
	s_nop 0
	v_lshrrev_b32_e32 v2, 3, v0
	s_and_b64 vcc, s[48:49], vcc
	s_lshl_b32 s4, s4, s79
	v_cndmask_b32_e32 v2, 0, v2, vcc
	v_add_u32_e32 v2, s4, v2
	v_ashrrev_i32_e32 v3, 31, v2
	v_lshlrev_b64 v[2:3], 10, v[2:3]
	v_lshl_add_u64 v[2:3], v[128:129], 0, v[2:3]
	global_load_dwordx4 v[78:81], v[2:3], off
	global_load_dwordx4 v[74:77], v[2:3], off offset:256
	global_load_dwordx4 v[70:73], v[2:3], off offset:512
	global_load_dwordx4 v[66:69], v[2:3], off offset:768
	v_add_u32_e32 v2, 32, v0
	v_cmp_gt_i32_e32 vcc, s54, v2
	v_cmp_lt_i32_e64 s[48:49], -1, v2
	v_lshrrev_b32_e32 v3, 3, v2
	s_and_b64 vcc, s[48:49], vcc
	v_cndmask_b32_e32 v2, 0, v3, vcc
	v_add_u32_e32 v2, s4, v2
	v_ashrrev_i32_e32 v3, 31, v2
	v_lshlrev_b64 v[2:3], 10, v[2:3]
	v_lshl_add_u64 v[2:3], v[128:129], 0, v[2:3]
	global_load_dwordx4 v[62:65], v[2:3], off
	global_load_dwordx4 v[58:61], v[2:3], off offset:256
	global_load_dwordx4 v[54:57], v[2:3], off offset:512
	global_load_dwordx4 v[50:53], v[2:3], off offset:768
	v_add_u32_e32 v2, s5, v140
	v_cmp_gt_i32_e32 vcc, s54, v2
	v_cmp_lt_i32_e64 s[48:49], -1, v2
	v_lshrrev_b32_e32 v3, 3, v2
	s_and_b64 vcc, s[48:49], vcc
	v_cndmask_b32_e32 v2, 0, v3, vcc
	v_add_u32_e32 v2, s4, v2
	v_ashrrev_i32_e32 v3, 31, v2
	v_lshlrev_b64 v[2:3], 10, v[2:3]
	v_lshl_add_u64 v[2:3], v[128:129], 0, v[2:3]
	global_load_dwordx4 v[46:49], v[2:3], off
	global_load_dwordx4 v[42:45], v[2:3], off offset:256
	global_load_dwordx4 v[38:41], v[2:3], off offset:512
	global_load_dwordx4 v[34:37], v[2:3], off offset:768
	v_add_u32_e32 v2, 0x60, v0
	v_cmp_gt_i32_e32 vcc, s54, v2
	v_cmp_lt_i32_e64 s[48:49], -1, v2
	v_lshrrev_b32_e32 v3, 3, v2
	s_and_b64 vcc, s[48:49], vcc
	v_cndmask_b32_e32 v2, 0, v3, vcc
	v_add_u32_e32 v2, s4, v2
	v_ashrrev_i32_e32 v3, 31, v2
	v_lshlrev_b64 v[2:3], 10, v[2:3]
	v_add_u32_e32 v0, 0x80, v0
	v_lshl_add_u64 v[2:3], v[128:129], 0, v[2:3]
	v_cmp_gt_i32_e32 vcc, s54, v0
	v_cmp_lt_i32_e64 s[48:49], -1, v0
	global_load_dwordx4 v[30:33], v[2:3], off
	global_load_dwordx4 v[26:29], v[2:3], off offset:256
	global_load_dwordx4 v[22:25], v[2:3], off offset:512
	global_load_dwordx4 v[18:21], v[2:3], off offset:768
	v_lshrrev_b32_e32 v2, 3, v0
	s_and_b64 vcc, s[48:49], vcc
	v_cndmask_b32_e32 v0, 0, v2, vcc
	v_add_u32_e32 v2, s4, v0
	v_ashrrev_i32_e32 v3, 31, v2
	v_lshlrev_b64 v[2:3], 10, v[2:3]
	v_lshl_add_u64 v[2:3], v[128:129], 0, v[2:3]
	global_load_dwordx4 v[14:17], v[2:3], off
	global_load_dwordx4 v[10:13], v[2:3], off offset:256
	global_load_dwordx4 v[6:9], v[2:3], off offset:512
	s_nop 0
	global_load_dwordx4 v[2:5], v[2:3], off offset:768
	s_sub_i32 s4, 64, s5
	s_sub_i32 s5, s42, s5
	v_max_i32_e32 v0, s4, v138
	v_min_i32_e32 v131, s5, v153
	v_sub_u32_e32 v131, v131, v0
	v_sub_u32_e32 v0, v140, v0
	v_cmp_le_u32_e32 vcc, v0, v131
	v_add_u32_e32 v134, 1, v0
	v_add_u32_e32 v156, 2, v0
	v_cndmask_b32_e32 v133, v241, v164, vcc
	v_cmp_le_u32_e32 vcc, v134, v131
	v_add_u32_e32 v157, 3, v0
	v_add_u32_e32 v158, 4, v0
	v_cndmask_b32_e32 v135, v241, v165, vcc
	v_cmp_le_u32_e32 vcc, v156, v131
	v_add_u32_e32 v159, 5, v0
	v_add_u32_e32 v160, 6, v0
	v_cndmask_b32_e32 v156, v241, v166, vcc
	v_cmp_le_u32_e32 vcc, v157, v131
	v_add_u32_e32 v161, 7, v0
	v_add_u32_e32 v162, 32, v0
	v_cndmask_b32_e32 v157, v241, v167, vcc
	v_cmp_le_u32_e32 vcc, v158, v131
	v_add_u32_e32 v163, 33, v0
	v_add_u32_e32 v164, 34, v0
	v_cndmask_b32_e32 v158, v241, v168, vcc
	v_cmp_le_u32_e32 vcc, v159, v131
	v_add_u32_e32 v165, 35, v0
	v_max3_f32 v134, v133, s58, v135
	v_cndmask_b32_e32 v159, v241, v169, vcc
	v_cmp_le_u32_e32 vcc, v160, v131
	v_max3_f32 v134, v134, v156, v157
	v_max3_f32 v134, v134, v158, v159
	v_cndmask_b32_e32 v160, v241, v170, vcc
	v_cmp_le_u32_e32 vcc, v161, v131
	s_mov_b64 s[48:49], -1
	s_nop 0
	v_cndmask_b32_e32 v161, v241, v171, vcc
	v_cmp_le_u32_e32 vcc, v162, v131
	v_max3_f32 v134, v134, v160, v161
	s_nop 0
	v_cndmask_b32_e32 v162, v241, v172, vcc
	v_cmp_le_u32_e32 vcc, v163, v131
	s_nop 1
	v_cndmask_b32_e32 v163, v241, v173, vcc
	v_cmp_le_u32_e32 vcc, v164, v131
	v_max3_f32 v134, v134, v162, v163
	s_nop 0
	v_cndmask_b32_e32 v164, v241, v174, vcc
	v_cmp_le_u32_e32 vcc, v165, v131
	v_add_u32_e32 v165, 36, v0
	s_nop 0
	v_cndmask_b32_e32 v167, v241, v175, vcc
	v_cmp_le_u32_e32 vcc, v165, v131
	v_add_u32_e32 v165, 37, v0
	v_max3_f32 v134, v134, v164, v167
	v_cndmask_b32_e32 v169, v241, v176, vcc
	v_cmp_le_u32_e32 vcc, v165, v131
	v_add_u32_e32 v165, 38, v0
	s_nop 0
	v_cndmask_b32_e32 v171, v241, v177, vcc
	v_cmp_le_u32_e32 vcc, v165, v131
	v_add_u32_e32 v165, 39, v0
; __device__ __forceinline__ void attn_unit(LAS unsigned char* lds, int b, int h, int blk, const bf16_t* Q, const bf16_t* Kb, const bf16_t* Vt1, const bf16_t* Vt4, const bf16_t* Vt16,
;                                           bf16_t* MIX, i64* ssq_a, int wid, int lane_in) {
;     ...
;             for (int g = 0; g < 2; ++g) {
;                 float m_ = -1e30f;
;                 int lo = 16 * g + qi, hi = 128 + 16 * g + qi; lo = lo > -ws_ ? lo : -ws_; hi = hi < L - 1 - ws_ ? hi : L - 1 - ws_;
;                 const int lo8 = lo - 8 * kq; const unsigned span = (unsigned)(hi - lo);
; #pragma unroll
;                 for (int t = 0; t < 10; ++t)
; #pragma unroll
;                     for (int i = 0; i < 4; ++i) {
;                         const int c = 32 * (t >> 1) + 4 * (t & 1) + i;
;                         const bool ok = (unsigned)(c - lo8) <= span;
;                         const float v = ok ? s[g][t][i] : -1e30f; s[g][t][i] = v; m_ = fmaxf(m_, v);
;                     }
;                 m_ = fmaxf(m_, __shfl_xor(m_, 16)); m_ = fmaxf(m_, __shfl_xor(m_, 32));
;                 float l_ = 0.f;
; #pragma unroll
;                 for (int t = 0; t < 10; ++t)
; #pragma unroll
;                     for (int i = 0; i < 4; ++i) { const float pv = __builtin_amdgcn_exp2f(s[g][t][i] - m_); s[g][t][i] = pv; l_ += pv; }
;                 l_ += __shfl_xor(l_, 16); l_ += __shfl_xor(l_, 32);
;                 mx[g] = m_; lsum[g] = l_;
	v_max3_f32 v134, v134, v169, v171
	v_cndmask_b32_e32 v172, v241, v178, vcc
	v_cmp_le_u32_e32 vcc, v165, v131
	v_add_u32_e32 v165, 64, v0
	s_nop 0
	v_cndmask_b32_e32 v175, v241, v179, vcc
	v_cmp_le_u32_e32 vcc, v165, v131
	v_add_u32_e32 v165, 0x41, v0
	v_max3_f32 v134, v134, v172, v175
	v_cndmask_b32_e32 v178, v241, v180, vcc
	v_cmp_le_u32_e32 vcc, v165, v131
	v_add_u32_e32 v165, 0x42, v0
	s_nop 0
	v_cndmask_b32_e32 v179, v241, v181, vcc
	v_cmp_le_u32_e32 vcc, v165, v131
	v_add_u32_e32 v165, 0x43, v0
	v_max3_f32 v134, v134, v178, v179
	v_cndmask_b32_e32 v181, v241, v182, vcc
	v_cmp_le_u32_e32 vcc, v165, v131
	v_add_u32_e32 v165, 0x44, v0
	s_nop 0
	v_cndmask_b32_e32 v182, v241, v183, vcc
	v_cmp_le_u32_e32 vcc, v165, v131
	v_add_u32_e32 v165, 0x45, v0
	v_max3_f32 v134, v134, v181, v182
	v_cndmask_b32_e32 v183, v241, v184, vcc
	v_cmp_le_u32_e32 vcc, v165, v131
	v_add_u32_e32 v165, 0x46, v0
	s_nop 0
	v_cndmask_b32_e32 v184, v241, v185, vcc
	v_cmp_le_u32_e32 vcc, v165, v131
	v_add_u32_e32 v165, 0x47, v0
	v_max3_f32 v134, v134, v183, v184
	v_cndmask_b32_e32 v185, v241, v186, vcc
	v_cmp_le_u32_e32 vcc, v165, v131
	v_add_u32_e32 v165, 0x60, v0
	s_nop 0
	v_cndmask_b32_e32 v186, v241, v187, vcc
	v_cmp_le_u32_e32 vcc, v165, v131
	v_add_u32_e32 v165, 0x61, v0
	v_max3_f32 v134, v134, v185, v186
	v_cndmask_b32_e32 v187, v241, v188, vcc
	v_cmp_le_u32_e32 vcc, v165, v131
	v_add_u32_e32 v165, 0x62, v0
	s_nop 0
	v_cndmask_b32_e32 v188, v241, v189, vcc
	v_cmp_le_u32_e32 vcc, v165, v131
	v_add_u32_e32 v165, 0x63, v0
	v_max3_f32 v134, v134, v187, v188
	v_cndmask_b32_e32 v189, v241, v190, vcc
	v_cmp_le_u32_e32 vcc, v165, v131
	v_add_u32_e32 v165, 0x64, v0
	s_nop 0
	v_cndmask_b32_e32 v190, v241, v191, vcc
	v_cmp_le_u32_e32 vcc, v165, v131
	v_add_u32_e32 v165, 0x65, v0
	v_max3_f32 v134, v134, v189, v190
	v_cndmask_b32_e32 v191, v241, v192, vcc
	v_cmp_le_u32_e32 vcc, v165, v131
	v_add_u32_e32 v165, 0x66, v0
	s_nop 0
	v_cndmask_b32_e32 v192, v241, v193, vcc
	v_cmp_le_u32_e32 vcc, v165, v131
	v_add_u32_e32 v165, 0x67, v0
	v_max3_f32 v134, v134, v191, v192
	v_cndmask_b32_e32 v193, v241, v194, vcc
	v_cmp_le_u32_e32 vcc, v165, v131
	v_add_u32_e32 v165, 0x80, v0
	s_nop 0
	v_cndmask_b32_e32 v194, v241, v195, vcc
	v_cmp_le_u32_e32 vcc, v165, v131
	v_add_u32_e32 v165, 0x81, v0
	v_max3_f32 v134, v134, v193, v194
	v_cndmask_b32_e32 v195, v241, v196, vcc
	v_cmp_le_u32_e32 vcc, v165, v131
	v_add_u32_e32 v165, 0x82, v0
	s_nop 0
	v_cndmask_b32_e32 v196, v241, v197, vcc
	v_cmp_le_u32_e32 vcc, v165, v131
	v_add_u32_e32 v165, 0x83, v0
	v_max3_f32 v134, v134, v195, v196
	v_cndmask_b32_e32 v197, v241, v198, vcc
	v_cmp_le_u32_e32 vcc, v165, v131
	v_add_u32_e32 v165, 0x84, v0
	s_nop 0
	v_cndmask_b32_e32 v198, v241, v199, vcc
	v_cmp_le_u32_e32 vcc, v165, v131
	v_add_u32_e32 v165, 0x85, v0
	v_max3_f32 v134, v134, v197, v198
	v_cndmask_b32_e32 v199, v241, v200, vcc
	v_cmp_le_u32_e32 vcc, v165, v131
	v_add_u32_e32 v165, 0x86, v0
	v_add_u32_e32 v0, 0x87, v0
	v_cndmask_b32_e32 v200, v241, v201, vcc
	v_cmp_le_u32_e32 vcc, v165, v131
	v_max3_f32 v134, v134, v199, v200
	s_nop 0
	v_cndmask_b32_e32 v201, v241, v202, vcc
	v_cmp_le_u32_e32 vcc, v0, v131
	s_nop 1
	v_cndmask_b32_e32 v202, v241, v203, vcc
	v_max3_f32 v0, v134, v201, v202
	ds_bpermute_b32 v131, v141, v0
	s_waitcnt lgkmcnt(0)
	v_max_f32_e32 v131, v131, v131
	v_max_f32_e32 v0, v0, v131
	ds_bpermute_b32 v131, v142, v0
	s_waitcnt lgkmcnt(0)
	v_max_f32_e32 v131, v131, v131
	v_max_f32_e32 v134, v0, v131
	v_sub_f32_e32 v131, v135, v134
	v_exp_f32_e32 v170, v131
	v_sub_f32_e32 v131, v156, v134
	v_exp_f32_e32 v173, v131
	v_sub_f32_e32 v131, v157, v134
	v_exp_f32_e32 v177, v131
	v_sub_f32_e32 v131, v158, v134
	v_exp_f32_e32 v180, v131
	v_sub_f32_e32 v131, v159, v134
	v_exp_f32_e32 v203, v131
	v_sub_f32_e32 v131, v160, v134
	v_exp_f32_e32 v204, v131
	v_sub_f32_e32 v131, v161, v134
	v_exp_f32_e32 v205, v131
	v_sub_f32_e32 v131, v162, v134
	v_exp_f32_e32 v158, v131
	v_sub_f32_e32 v131, v163, v134
	v_exp_f32_e32 v166, v131
	v_sub_f32_e32 v131, v164, v134
	v_exp_f32_e32 v168, v131
	v_sub_f32_e32 v131, v167, v134
	v_exp_f32_e32 v174, v131
	v_sub_f32_e32 v131, v169, v134
	v_exp_f32_e32 v176, v131
	v_sub_f32_e32 v131, v171, v134
	v_exp_f32_e32 v206, v131
	v_sub_f32_e32 v131, v172, v134
	v_exp_f32_e32 v207, v131
	v_sub_f32_e32 v131, v175, v134
	v_sub_f32_e32 v0, v133, v134
	v_exp_f32_e32 v208, v131
	v_sub_f32_e32 v131, v178, v134
	v_exp_f32_e32 v165, v0
	v_exp_f32_e32 v135, v131
	v_sub_f32_e32 v131, v179, v134
	v_exp_f32_e32 v161, v131
	v_sub_f32_e32 v131, v181, v134
	v_exp_f32_e32 v163, v131
	v_sub_f32_e32 v131, v182, v134
	v_exp_f32_e32 v169, v131
	v_sub_f32_e32 v131, v183, v134
	v_add_f32_e32 v0, 0, v165
	v_exp_f32_e32 v172, v131
	v_sub_f32_e32 v131, v184, v134
	v_add_f32_e32 v0, v170, v0
	v_exp_f32_e32 v179, v131
	v_sub_f32_e32 v131, v185, v134
	v_add_f32_e32 v0, v173, v0
	v_exp_f32_e32 v181, v131
	v_sub_f32_e32 v131, v186, v134
	v_max_i32_e32 v185, s4, v154
	v_min_i32_e32 v186, s5, v155
	v_add_f32_e32 v0, v177, v0
	v_sub_u32_e32 v186, v186, v185
	v_sub_u32_e32 v185, v140, v185
	v_add_f32_e32 v0, v180, v0
	v_exp_f32_e32 v182, v131
	v_sub_f32_e32 v131, v187, v134
	v_cmp_le_u32_e32 vcc, v185, v186
	v_add_u32_e32 v187, 1, v185
	v_add_f32_e32 v0, v203, v0
	v_sub_f32_e32 v133, v188, v134
	v_cndmask_b32_e32 v118, v241, v118, vcc
	v_cmp_le_u32_e32 vcc, v187, v186
	v_add_u32_e32 v188, 2, v185
	v_add_f32_e32 v0, v204, v0
	v_cndmask_b32_e32 v119, v241, v119, vcc
	v_cmp_le_u32_e32 vcc, v188, v186
	v_add_u32_e32 v188, 3, v185
	v_add_f32_e32 v0, v205, v0
	v_cndmask_b32_e32 v120, v241, v120, vcc
	v_cmp_le_u32_e32 vcc, v188, v186
	v_add_u32_e32 v188, 4, v185
; __device__ __forceinline__ void attn_unit(LAS unsigned char* lds, int b, int h, int blk, const bf16_t* Q, const bf16_t* Kb, const bf16_t* Vt1, const bf16_t* Vt4, const bf16_t* Vt16,
;                                           bf16_t* MIX, i64* ssq_a, int wid, int lane_in) {
;     ...
;             for (int g = 0; g < 2; ++g) {
;                 float m_ = -1e30f;
;                 int lo = 16 * g + qi, hi = 128 + 16 * g + qi; lo = lo > -ws_ ? lo : -ws_; hi = hi < L - 1 - ws_ ? hi : L - 1 - ws_;
;                 const int lo8 = lo - 8 * kq; const unsigned span = (unsigned)(hi - lo);
; #pragma unroll
;                 for (int t = 0; t < 10; ++t)
; #pragma unroll
;                     for (int i = 0; i < 4; ++i) {
;                         const int c = 32 * (t >> 1) + 4 * (t & 1) + i;
;                         const bool ok = (unsigned)(c - lo8) <= span;
;                         const float v = ok ? s[g][t][i] : -1e30f; s[g][t][i] = v; m_ = fmaxf(m_, v);
;                     }
;                 m_ = fmaxf(m_, __shfl_xor(m_, 16)); m_ = fmaxf(m_, __shfl_xor(m_, 32));
;                 float l_ = 0.f;
; #pragma unroll
;                 for (int t = 0; t < 10; ++t)
; #pragma unroll
;                     for (int i = 0; i < 4; ++i) { const float pv = __builtin_amdgcn_exp2f(s[g][t][i] - m_); s[g][t][i] = pv; l_ += pv; }
;                 l_ += __shfl_xor(l_, 16); l_ += __shfl_xor(l_, 32);
;                 mx[g] = m_; lsum[g] = l_;
	v_add_f32_e32 v0, v158, v0
	v_cndmask_b32_e32 v121, v241, v121, vcc
	v_cmp_le_u32_e32 vcc, v188, v186
	v_add_u32_e32 v188, 5, v185
	v_add_f32_e32 v0, v166, v0
	v_cndmask_b32_e32 v114, v241, v114, vcc
	v_cmp_le_u32_e32 vcc, v188, v186
	v_add_u32_e32 v188, 6, v185
	v_add_f32_e32 v0, v168, v0
	v_cndmask_b32_e32 v115, v241, v115, vcc
	v_cmp_le_u32_e32 vcc, v188, v186
	v_add_u32_e32 v188, 7, v185
	v_add_f32_e32 v0, v174, v0
	v_cndmask_b32_e32 v116, v241, v116, vcc
	v_cmp_le_u32_e32 vcc, v188, v186
	v_add_u32_e32 v188, 32, v185
	v_add_f32_e32 v0, v176, v0
	v_cndmask_b32_e32 v117, v241, v117, vcc
	v_cmp_le_u32_e32 vcc, v188, v186
	v_add_u32_e32 v188, 33, v185
	v_add_f32_e32 v0, v206, v0
	v_cndmask_b32_e32 v110, v241, v110, vcc
	v_cmp_le_u32_e32 vcc, v188, v186
	v_add_u32_e32 v188, 34, v185
	v_add_f32_e32 v0, v207, v0
	v_cndmask_b32_e32 v111, v241, v111, vcc
	v_cmp_le_u32_e32 vcc, v188, v186
	v_add_u32_e32 v188, 35, v185
	v_add_f32_e32 v0, v208, v0
	v_cndmask_b32_e32 v112, v241, v112, vcc
	v_cmp_le_u32_e32 vcc, v188, v186
	v_add_u32_e32 v188, 36, v185
	v_add_f32_e32 v0, v135, v0
	v_cndmask_b32_e32 v113, v241, v113, vcc
	v_cmp_le_u32_e32 vcc, v188, v186
	v_add_u32_e32 v188, 37, v185
	v_add_f32_e32 v0, v161, v0
	v_cndmask_b32_e32 v106, v241, v106, vcc
	v_cmp_le_u32_e32 vcc, v188, v186
	v_add_u32_e32 v188, 38, v185
	v_add_f32_e32 v0, v163, v0
	v_cndmask_b32_e32 v107, v241, v107, vcc
	v_cmp_le_u32_e32 vcc, v188, v186
	v_add_u32_e32 v188, 39, v185
	v_add_f32_e32 v0, v169, v0
	v_max3_f32 v187, v118, s58, v119
	v_cndmask_b32_e32 v108, v241, v108, vcc
	v_cmp_le_u32_e32 vcc, v188, v186
	v_add_u32_e32 v188, 64, v185
	v_add_f32_e32 v0, v172, v0
	v_exp_f32_e32 v131, v131
	v_max3_f32 v187, v187, v120, v121
	v_cndmask_b32_e32 v109, v241, v109, vcc
	v_cmp_le_u32_e32 vcc, v188, v186
	v_add_f32_e32 v0, v179, v0
	v_exp_f32_e32 v157, v133
	v_sub_f32_e32 v133, v189, v134
	v_max3_f32 v187, v187, v114, v115
	v_cndmask_b32_e32 v188, v241, v102, vcc
	v_add_u32_e32 v102, 0x41, v185
	v_add_f32_e32 v0, v181, v0
	v_exp_f32_e32 v159, v133
	v_sub_f32_e32 v133, v190, v134
	v_max3_f32 v187, v187, v116, v117
	v_cmp_le_u32_e32 vcc, v102, v186
	v_add_f32_e32 v0, v182, v0
	v_exp_f32_e32 v164, v133
	v_sub_f32_e32 v133, v191, v134
	v_max3_f32 v187, v187, v110, v111
	v_cndmask_b32_e32 v189, v241, v103, vcc
	v_add_u32_e32 v103, 0x42, v185
	v_add_f32_e32 v0, v131, v0
	v_exp_f32_e32 v167, v133
	v_max3_f32 v187, v187, v112, v113
	v_cmp_le_u32_e32 vcc, v103, v186
	v_add_u32_e32 v103, 0x43, v185
	v_add_f32_e32 v0, v157, v0
	v_max3_f32 v187, v187, v106, v107
	v_cndmask_b32_e32 v104, v241, v104, vcc
	v_cmp_le_u32_e32 vcc, v103, v186
	v_add_u32_e32 v103, 0x44, v185
	v_add_f32_e32 v0, v159, v0
	v_max3_f32 v187, v187, v108, v109
	v_cndmask_b32_e32 v105, v241, v105, vcc
	v_cmp_le_u32_e32 vcc, v103, v186
	v_add_f32_e32 v0, v164, v0
	v_max3_f32 v102, v187, v188, v189
	v_cndmask_b32_e32 v187, v241, v98, vcc
	v_add_u32_e32 v98, 0x45, v185
	v_add_f32_e32 v133, v167, v0
	v_sub_f32_e32 v0, v192, v134
	v_cmp_le_u32_e32 vcc, v98, v186
	v_exp_f32_e32 v175, v0
	v_sub_f32_e32 v0, v193, v134
	v_cndmask_b32_e32 v190, v241, v99, vcc
	v_add_u32_e32 v99, 0x46, v185
	v_exp_f32_e32 v178, v0
	v_sub_f32_e32 v0, v194, v134
	v_cmp_le_u32_e32 vcc, v99, v186
	v_add_u32_e32 v99, 0x47, v185
	v_exp_f32_e32 v183, v0
	v_sub_f32_e32 v0, v195, v134
	v_cndmask_b32_e32 v191, v241, v100, vcc
	v_cmp_le_u32_e32 vcc, v99, v186
	v_add_u32_e32 v99, 0x60, v185
	v_exp_f32_e32 v0, v0
	v_cndmask_b32_e32 v192, v241, v101, vcc
	v_cmp_le_u32_e32 vcc, v99, v186
	v_add_f32_e32 v133, v175, v133
	v_add_f32_e32 v133, v178, v133
	v_cndmask_b32_e32 v193, v241, v94, vcc
	v_add_u32_e32 v94, 0x61, v185
	v_cmp_le_u32_e32 vcc, v94, v186
	v_add_f32_e32 v133, v183, v133
	v_add_f32_e32 v171, v0, v133
	v_cndmask_b32_e32 v194, v241, v95, vcc
	v_add_u32_e32 v95, 0x62, v185
	v_sub_f32_e32 v133, v196, v134
	v_cmp_le_u32_e32 vcc, v95, v186
	v_add_u32_e32 v95, 0x63, v185
	v_exp_f32_e32 v133, v133
	v_sub_f32_e32 v156, v197, v134
	v_cndmask_b32_e32 v195, v241, v96, vcc
	v_cmp_le_u32_e32 vcc, v95, v186
	v_add_u32_e32 v95, 0x64, v185
	v_exp_f32_e32 v156, v156
	v_sub_f32_e32 v160, v198, v134
	v_cndmask_b32_e32 v196, v241, v97, vcc
	v_cmp_le_u32_e32 vcc, v95, v186
	v_exp_f32_e32 v160, v160
	v_sub_f32_e32 v162, v199, v134
	v_cndmask_b32_e32 v197, v241, v90, vcc
	v_add_u32_e32 v90, 0x65, v185
	v_exp_f32_e32 v162, v162
	v_cmp_le_u32_e32 vcc, v90, v186
	v_add_f32_e32 v171, v133, v171
	v_add_f32_e32 v171, v156, v171
	v_cndmask_b32_e32 v198, v241, v91, vcc
	v_add_u32_e32 v91, 0x66, v185
	v_cmp_le_u32_e32 vcc, v91, v186
	v_add_u32_e32 v91, 0x67, v185
	v_add_f32_e32 v171, v160, v171
	v_cndmask_b32_e32 v199, v241, v92, vcc
	v_cmp_le_u32_e32 vcc, v91, v186
	v_add_u32_e32 v91, 0x80, v185
	v_add_f32_e32 v184, v162, v171
	v_sub_f32_e32 v171, v200, v134
	v_cndmask_b32_e32 v200, v241, v93, vcc
	v_cmp_le_u32_e32 vcc, v91, v186
	v_max3_f32 v102, v102, v104, v105
	v_max3_f32 v98, v102, v187, v190
	v_cndmask_b32_e32 v209, v241, v86, vcc
	v_add_u32_e32 v86, 0x81, v185
	v_cmp_le_u32_e32 vcc, v86, v186
	v_max3_f32 v98, v98, v191, v192
	v_max3_f32 v94, v98, v193, v194
	v_cndmask_b32_e32 v215, v241, v87, vcc
	v_add_u32_e32 v87, 0x82, v185
	v_cmp_le_u32_e32 vcc, v87, v186
	v_add_u32_e32 v87, 0x83, v185
	v_max3_f32 v94, v94, v195, v196
	v_cndmask_b32_e32 v224, v241, v88, vcc
	v_cmp_le_u32_e32 vcc, v87, v186
	v_add_u32_e32 v87, 0x84, v185
	v_max3_f32 v90, v94, v197, v198
	v_cndmask_b32_e32 v225, v241, v89, vcc
	v_cmp_le_u32_e32 vcc, v87, v186
	v_max3_f32 v90, v90, v199, v200
	v_max3_f32 v86, v90, v209, v215
	v_cndmask_b32_e32 v226, v241, v82, vcc
	v_add_u32_e32 v82, 0x85, v185
	v_cmp_le_u32_e32 vcc, v82, v186
	v_max3_f32 v86, v86, v224, v225
	v_exp_f32_e32 v171, v171
	v_cndmask_b32_e32 v83, v241, v83, vcc
	v_max3_f32 v82, v86, v226, v83
	v_add_u32_e32 v86, 0x86, v185
	v_cmp_le_u32_e32 vcc, v86, v186
	s_nop 1
	v_cndmask_b32_e32 v227, v241, v84, vcc
	v_add_u32_e32 v84, 0x87, v185
	v_cmp_le_u32_e32 vcc, v84, v186
	s_nop 1
	v_cndmask_b32_e32 v185, v241, v85, vcc
	v_max3_f32 v82, v82, v227, v185
	ds_bpermute_b32 v84, v141, v82
	v_sub_f32_e32 v85, v201, v134
	v_exp_f32_e32 v186, v85
	v_sub_f32_e32 v85, v202, v134
	v_exp_f32_e32 v201, v85
	s_waitcnt lgkmcnt(0)
; __device__ __forceinline__ unsigned cvt_pk_bf16(float lo, float hi) { unsigned r; asm volatile("v_cvt_pk_bf16_f32 %0, %1, %2" : "=v"(r) : "v"(lo), "v"(hi)); return r; }
; __device__ __forceinline__ void attn_unit(LAS unsigned char* lds, int b, int h, int blk, const bf16_t* Q, const bf16_t* Kb, const bf16_t* Vt1, const bf16_t* Vt4, const bf16_t* Vt16,
;                                           bf16_t* MIX, i64* ssq_a, int wid, int lane_in) {
;     ...
;                 m_ = fmaxf(m_, __shfl_xor(m_, 16)); m_ = fmaxf(m_, __shfl_xor(m_, 32));
;                 float l_ = 0.f;
; #pragma unroll
;                 for (int t = 0; t < 10; ++t)
; #pragma unroll
;                     for (int i = 0; i < 4; ++i) { const float pv = __builtin_amdgcn_exp2f(s[g][t][i] - m_); s[g][t][i] = pv; l_ += pv; }
;                 l_ += __shfl_xor(l_, 16); l_ += __shfl_xor(l_, 32);
;                 mx[g] = m_; lsum[g] = l_;
;             }
;             f32x4 o[2][4];
; #pragma unroll
;             for (int g = 0; g < 2; ++g)
; #pragma unroll
;                 for (int dt = 0; dt < 4; ++dt) o[g][dt] = (f32x4){0.f, 0.f, 0.f, 0.f};
; #pragma unroll
;             for (int c = 0; c < 5; ++c)
; #pragma unroll
;                 for (int g = 0; g < 2; ++g) {
;                     union { u32x4 u; bf16x8 v; } pf;
;                     pf.u.x = cvt_pk_bf16(s[g][2 * c][0], s[g][2 * c][1]); pf.u.y = cvt_pk_bf16(s[g][2 * c][2], s[g][2 * c][3]);
;                     pf.u.z = cvt_pk_bf16(s[g][2 * c + 1][0], s[g][2 * c + 1][1]); pf.u.w = cvt_pk_bf16(s[g][2 * c + 1][2], s[g][2 * c + 1][3]);
; #pragma unroll
;                     for (int dt = 0; dt < 4; ++dt) o[g][dt] = __builtin_amdgcn_mfma_f32_16x16x32_bf16(vf[c][dt], pf.v, o[g][dt], 0, 0, 0);
;                 }
	v_max_f32_e32 v84, v84, v84
	v_max_f32_e32 v82, v82, v84
	ds_bpermute_b32 v84, v142, v82
	v_add_f32_e32 v85, v171, v184
	v_add_f32_e32 v85, v186, v85
	v_add_f32_e32 v85, v201, v85
	ds_bpermute_b32 v86, v141, v85
	s_waitcnt lgkmcnt(1)
	v_max_f32_e32 v84, v84, v84
	v_max_f32_e32 v82, v82, v84
	v_sub_f32_e32 v84, v118, v82
	v_exp_f32_e32 v100, v84
	v_sub_f32_e32 v84, v119, v82
	v_exp_f32_e32 v101, v84
	s_waitcnt lgkmcnt(0)
	v_add_f32_e32 v118, v85, v86
	v_sub_f32_e32 v85, v120, v82
	v_exp_f32_e32 v102, v85
	v_sub_f32_e32 v85, v121, v82
	v_exp_f32_e32 v103, v85
	v_sub_f32_e32 v85, v114, v82
	v_add_f32_e32 v84, 0, v100
	v_exp_f32_e32 v114, v85
	v_sub_f32_e32 v85, v115, v82
	v_add_f32_e32 v84, v101, v84
	v_exp_f32_e32 v115, v85
	v_sub_f32_e32 v85, v116, v82
	v_add_f32_e32 v84, v102, v84
	v_exp_f32_e32 v116, v85
	v_sub_f32_e32 v85, v117, v82
	v_add_f32_e32 v84, v103, v84
	v_exp_f32_e32 v117, v85
	v_sub_f32_e32 v85, v110, v82
	v_add_f32_e32 v84, v114, v84
	v_exp_f32_e32 v110, v85
	v_sub_f32_e32 v85, v111, v82
	v_add_f32_e32 v84, v115, v84
	v_exp_f32_e32 v111, v85
	v_add_f32_e32 v84, v116, v84
	v_add_f32_e32 v84, v117, v84
	v_add_f32_e32 v84, v110, v84
	v_add_f32_e32 v92, v111, v84
	v_sub_f32_e32 v84, v112, v82
	v_exp_f32_e32 v112, v84
	v_sub_f32_e32 v84, v113, v82
	v_exp_f32_e32 v113, v84
	v_sub_f32_e32 v84, v106, v82
	v_exp_f32_e32 v106, v84
	v_sub_f32_e32 v96, v107, v82
	v_exp_f32_e32 v107, v96
	v_sub_f32_e32 v108, v108, v82
	v_add_f32_e32 v92, v112, v92
	v_exp_f32_e32 v108, v108
	v_sub_f32_e32 v109, v109, v82
	v_cvt_pk_bf16_f32 v84, v165, v170
	v_cvt_pk_bf16_f32 v85, v173, v177
	v_cvt_pk_bf16_f32 v86, v180, v203
	v_cvt_pk_bf16_f32 v87, v204, v205
	v_add_f32_e32 v92, v113, v92
	v_exp_f32_e32 v109, v109
	v_cvt_pk_bf16_f32 v100, v100, v101
	v_cvt_pk_bf16_f32 v101, v102, v103
	v_cvt_pk_bf16_f32 v102, v114, v115
	v_sub_f32_e32 v115, v188, v82
	v_add_f32_e32 v120, v106, v92
	v_cvt_pk_bf16_f32 v103, v116, v117
	v_exp_f32_e32 v115, v115
	v_sub_f32_e32 v116, v189, v82
	s_waitcnt vmcnt(19)
	v_mfma_f32_16x16x32_bf16 v[88:91], v[78:81], v[84:87], 0
	v_add_f32_e32 v114, v107, v120
	v_exp_f32_e32 v116, v116
	v_sub_f32_e32 v104, v104, v82
	s_waitcnt vmcnt(18)
	v_mfma_f32_16x16x32_bf16 v[92:95], v[74:77], v[84:87], 0
	v_add_f32_e32 v114, v108, v114
	v_exp_f32_e32 v104, v104
	v_sub_f32_e32 v105, v105, v82
	s_waitcnt vmcnt(17)
	v_mfma_f32_16x16x32_bf16 v[96:99], v[70:73], v[84:87], 0
	v_add_f32_e32 v114, v109, v114
	v_exp_f32_e32 v105, v105
	v_sub_f32_e32 v117, v187, v82
	s_waitcnt vmcnt(16)
	v_mfma_f32_16x16x32_bf16 v[84:87], v[66:69], v[84:87], 0
	v_add_f32_e32 v114, v115, v114
	v_exp_f32_e32 v117, v117
	v_sub_f32_e32 v120, v190, v82
	v_mfma_f32_16x16x32_bf16 v[74:77], v[74:77], v[100:103], 0
	v_add_f32_e32 v114, v116, v114
	v_exp_f32_e32 v120, v120
	v_add_f32_e32 v114, v104, v114
	v_mfma_f32_16x16x32_bf16 v[78:81], v[78:81], v[100:103], 0
	ds_bpermute_b32 v119, v142, v118
	s_and_b64 vcc, s[52:53], exec
	v_mfma_f32_16x16x32_bf16 v[70:73], v[70:73], v[100:103], 0
	v_mfma_f32_16x16x32_bf16 v[66:69], v[66:69], v[100:103], 0
	v_cvt_pk_bf16_f32 v100, v158, v166
	v_cvt_pk_bf16_f32 v101, v168, v174
	v_cvt_pk_bf16_f32 v102, v176, v206
	v_cvt_pk_bf16_f32 v103, v207, v208
	s_waitcnt vmcnt(15)
	v_mfma_f32_16x16x32_bf16 v[88:91], v[62:65], v[100:103], v[88:91]
	s_waitcnt vmcnt(14)
	v_mfma_f32_16x16x32_bf16 v[92:95], v[58:61], v[100:103], v[92:95]
	s_waitcnt vmcnt(13)
	v_mfma_f32_16x16x32_bf16 v[96:99], v[54:57], v[100:103], v[96:99]
	s_waitcnt vmcnt(12)
	v_mfma_f32_16x16x32_bf16 v[84:87], v[50:53], v[100:103], v[84:87]
	v_cvt_pk_bf16_f32 v100, v110, v111
	v_cvt_pk_bf16_f32 v101, v112, v113
	v_cvt_pk_bf16_f32 v102, v106, v107
	v_cvt_pk_bf16_f32 v103, v108, v109
	s_nop 0
	v_mfma_f32_16x16x32_bf16 v[58:61], v[58:61], v[100:103], v[74:77]
	s_nop 2
	v_sub_f32_e32 v74, v191, v82
	v_exp_f32_e32 v106, v74
	v_mfma_f32_16x16x32_bf16 v[62:65], v[62:65], v[100:103], v[78:81]
	v_sub_f32_e32 v74, v192, v82
	v_exp_f32_e32 v107, v74
	s_nop 0
	v_add_f32_e32 v78, v105, v114
	v_add_f32_e32 v78, v117, v78
	v_add_f32_e32 v78, v120, v78
	v_mfma_f32_16x16x32_bf16 v[54:57], v[54:57], v[100:103], v[70:73]
	v_add_f32_e32 v74, v106, v78
	v_sub_f32_e32 v78, v194, v82
	v_add_f32_e32 v74, v107, v74
	v_sub_f32_e32 v70, v193, v82
	v_exp_f32_e32 v108, v70
	v_mfma_f32_16x16x32_bf16 v[50:53], v[50:53], v[100:103], v[66:69]
	v_cvt_pk_bf16_f32 v66, v135, v161
	v_cvt_pk_bf16_f32 v67, v163, v169
	v_cvt_pk_bf16_f32 v68, v172, v179
	v_cvt_pk_bf16_f32 v69, v181, v182
	s_waitcnt lgkmcnt(0)
	v_add_f32_e32 v135, v118, v119
	s_waitcnt vmcnt(11)
	v_mfma_f32_16x16x32_bf16 v[70:73], v[46:49], v[66:69], v[88:91]
	s_nop 2
	v_exp_f32_e32 v89, v78
	v_sub_f32_e32 v90, v195, v82
	v_exp_f32_e32 v90, v90
	v_sub_f32_e32 v91, v196, v82
	v_add_f32_e32 v88, v108, v74
	s_waitcnt vmcnt(10)
	v_mfma_f32_16x16x32_bf16 v[74:77], v[42:45], v[66:69], v[92:95]
	v_exp_f32_e32 v91, v91
	s_waitcnt vmcnt(9)
	v_mfma_f32_16x16x32_bf16 v[78:81], v[38:41], v[66:69], v[96:99]
	s_waitcnt vmcnt(8)
; __device__ __forceinline__ unsigned cvt_pk_bf16(float lo, float hi) { unsigned r; asm volatile("v_cvt_pk_bf16_f32 %0, %1, %2" : "=v"(r) : "v"(lo), "v"(hi)); return r; }
; #define LAS __attribute__((address_space(3)))
; __device__ __forceinline__ void attn_unit(LAS unsigned char* lds, int b, int h, int blk, const bf16_t* Q, const bf16_t* Kb, const bf16_t* Vt1, const bf16_t* Vt4, const bf16_t* Vt16,
;                                           bf16_t* MIX, i64* ssq_a, int wid, int lane_in) {
;     ...
; #pragma unroll
;             for (int c = 0; c < 5; ++c)
; #pragma unroll
;                 for (int g = 0; g < 2; ++g) {
;                     union { u32x4 u; bf16x8 v; } pf;
;                     pf.u.x = cvt_pk_bf16(s[g][2 * c][0], s[g][2 * c][1]); pf.u.y = cvt_pk_bf16(s[g][2 * c][2], s[g][2 * c][3]);
;                     pf.u.z = cvt_pk_bf16(s[g][2 * c + 1][0], s[g][2 * c + 1][1]); pf.u.w = cvt_pk_bf16(s[g][2 * c + 1][2], s[g][2 * c + 1][3]);
; #pragma unroll
;                     for (int dt = 0; dt < 4; ++dt) o[g][dt] = __builtin_amdgcn_mfma_f32_16x16x32_bf16(vf[c][dt], pf.v, o[g][dt], 0, 0, 0);
;                 }
; #pragma unroll
;             for (int g = 0; g < 2; ++g) {
;                 const int tl = qtok[g] - T0;
;                 LAS float* orow = Oacc + tl * OP + 4 * kq;
;                 if (p == 0) {
; #pragma unroll
;                     for (int dt = 0; dt < 4; ++dt) *(LAS f32x4*)(orow + 16 * dt) = o[g][dt];
;                     if (kq == 0) { Ml[2 * tl] = mx[g]; Ml[2 * tl + 1] = lsum[g]; }
;                 } else {
;                     const float mo = Ml[2 * tl], lo = Ml[2 * tl + 1];
;                     const float mn = fmaxf(mo, mx[g]), fa = __builtin_amdgcn_exp2f(mo - mn), fb = __builtin_amdgcn_exp2f(mx[g] - mn);
;                     f32x4 om[4];
; #pragma unroll
;                     for (int dt = 0; dt < 4; ++dt) om[dt] = *(const LAS f32x4*)(orow + 16 * dt) * fa + o[g][dt] * fb;
;                     const float ln = lo * fa + lsum[g] * fb;
;                     asm volatile("s_waitcnt lgkmcnt(0)" ::: "memory");
; #pragma unroll
;                     for (int dt = 0; dt < 4; ++dt) *(LAS f32x4*)(orow + 16 * dt) = om[dt];
;                     if (kq == 0) { Ml[2 * tl] = mn; Ml[2 * tl + 1] = ln; }
;                 }
	v_mfma_f32_16x16x32_bf16 v[66:69], v[34:37], v[66:69], v[84:87]
	v_cvt_pk_bf16_f32 v84, v115, v116
	v_cvt_pk_bf16_f32 v85, v104, v105
	v_cvt_pk_bf16_f32 v86, v117, v120
	v_cvt_pk_bf16_f32 v87, v106, v107
	s_nop 0
	v_mfma_f32_16x16x32_bf16 v[42:45], v[42:45], v[84:87], v[58:61]
	s_nop 2
	v_sub_f32_e32 v58, v197, v82
	v_mfma_f32_16x16x32_bf16 v[46:49], v[46:49], v[84:87], v[62:65]
	s_nop 2
	v_add_f32_e32 v62, v89, v88
	v_exp_f32_e32 v88, v58
	v_add_f32_e32 v62, v90, v62
	v_sub_f32_e32 v58, v198, v82
	v_add_f32_e32 v62, v91, v62
	v_mfma_f32_16x16x32_bf16 v[38:41], v[38:41], v[84:87], v[54:57]
	v_exp_f32_e32 v92, v58
	v_add_f32_e32 v58, v88, v62
	v_sub_f32_e32 v62, v200, v82
	v_sub_f32_e32 v54, v199, v82
	v_exp_f32_e32 v93, v54
	v_mfma_f32_16x16x32_bf16 v[34:37], v[34:37], v[84:87], v[50:53]
	v_cvt_pk_bf16_f32 v50, v131, v157
	v_cvt_pk_bf16_f32 v51, v159, v164
	v_cvt_pk_bf16_f32 v52, v167, v175
	v_cvt_pk_bf16_f32 v53, v178, v183
	v_add_f32_e32 v58, v92, v58
	s_waitcnt vmcnt(7)
	v_mfma_f32_16x16x32_bf16 v[54:57], v[30:33], v[50:53], v[70:73]
	s_nop 2
	v_exp_f32_e32 v71, v62
	v_sub_f32_e32 v72, v209, v82
	v_exp_f32_e32 v72, v72
	v_sub_f32_e32 v73, v215, v82
	v_add_f32_e32 v70, v93, v58
	s_waitcnt vmcnt(6)
	v_mfma_f32_16x16x32_bf16 v[58:61], v[26:29], v[50:53], v[74:77]
	v_exp_f32_e32 v73, v73
	s_waitcnt vmcnt(5)
	v_mfma_f32_16x16x32_bf16 v[62:65], v[22:25], v[50:53], v[78:81]
	s_waitcnt vmcnt(4)
	v_mfma_f32_16x16x32_bf16 v[50:53], v[18:21], v[50:53], v[66:69]
	v_cvt_pk_bf16_f32 v66, v108, v89
	v_cvt_pk_bf16_f32 v67, v90, v91
	v_cvt_pk_bf16_f32 v68, v88, v92
	v_cvt_pk_bf16_f32 v69, v93, v71
	s_nop 0
	v_mfma_f32_16x16x32_bf16 v[42:45], v[26:29], v[66:69], v[42:45]
	v_sub_f32_e32 v26, v224, v82
	v_mfma_f32_16x16x32_bf16 v[46:49], v[30:33], v[66:69], v[46:49]
	v_add_f32_e32 v30, v71, v70
	v_exp_f32_e32 v71, v26
	v_sub_f32_e32 v26, v225, v82
	v_mfma_f32_16x16x32_bf16 v[38:41], v[22:25], v[66:69], v[38:41]
	v_exp_f32_e32 v74, v26
	v_sub_f32_e32 v22, v226, v82
	v_add_f32_e32 v30, v72, v30
	v_exp_f32_e32 v75, v22
	v_sub_f32_e32 v26, v83, v82
	v_add_f32_e32 v70, v73, v30
	v_mfma_f32_16x16x32_bf16 v[34:37], v[18:21], v[66:69], v[34:37]
	v_cvt_pk_bf16_f32 v30, v0, v133
	v_cvt_pk_bf16_f32 v31, v156, v160
	v_cvt_pk_bf16_f32 v32, v162, v171
	v_cvt_pk_bf16_f32 v33, v186, v201
	v_add_f32_e32 v0, v71, v70
	s_waitcnt vmcnt(3)
	v_mfma_f32_16x16x32_bf16 v[18:21], v[14:17], v[30:33], v[54:57]
	v_add_f32_e32 v0, v74, v0
	v_add_f32_e32 v0, v75, v0
	s_nop 0
	v_exp_f32_e32 v54, v26
	v_sub_f32_e32 v55, v227, v82
	v_exp_f32_e32 v55, v55
	v_sub_f32_e32 v56, v185, v82
	v_exp_f32_e32 v56, v56
	v_add_f32_e32 v0, v54, v0
	v_add_f32_e32 v0, v55, v0
	s_waitcnt vmcnt(2)
	v_mfma_f32_16x16x32_bf16 v[22:25], v[10:13], v[30:33], v[58:61]
	v_add_f32_e32 v0, v56, v0
	s_waitcnt vmcnt(1)
	v_mfma_f32_16x16x32_bf16 v[26:29], v[6:9], v[30:33], v[62:65]
	s_waitcnt vmcnt(0)
	v_mfma_f32_16x16x32_bf16 v[30:33], v[2:5], v[30:33], v[50:53]
	v_cvt_pk_bf16_f32 v50, v72, v73
	v_cvt_pk_bf16_f32 v51, v71, v74
	v_cvt_pk_bf16_f32 v52, v75, v54
	v_cvt_pk_bf16_f32 v53, v55, v56
	s_nop 0
	v_mfma_f32_16x16x32_bf16 v[10:13], v[10:13], v[50:53], v[42:45]
	s_nop 2
	ds_bpermute_b32 v42, v141, v0
	v_mfma_f32_16x16x32_bf16 v[6:9], v[6:9], v[50:53], v[38:41]
	s_waitcnt lgkmcnt(0)
	s_nop 1
	v_add_f32_e32 v38, v0, v42
	ds_bpermute_b32 v39, v142, v38
	v_mfma_f32_16x16x32_bf16 v[14:17], v[14:17], v[50:53], v[46:49]
	v_subrev_u32_e32 v40, s18, v132
	v_mul_lo_u32 v0, v40, s59
	v_add_u32_e32 v41, v143, v0
	v_mfma_f32_16x16x32_bf16 v[2:5], v[2:5], v[50:53], v[34:37]
	s_cbranch_vccz .LBB0_1094
	v_lshlrev_b32_e32 v0, 3, v40
	v_add_u32_e32 v0, 0, v0
	v_add_u32_e32 v42, 0x22000, v0
	ds_read_b64 v[34:35], v42
	v_max_f32_e32 v0, v134, v134
	ds_read_b128 v[44:47], v41
	ds_read_b128 v[48:51], v41 offset:64
	s_waitcnt lgkmcnt(2)
	v_max_f32_e32 v36, v34, v34
	v_max_f32_e32 v36, v36, v0
	v_sub_f32_e32 v0, v134, v36
	v_exp_f32_e32 v0, v0
	v_sub_f32_e32 v34, v34, v36
	v_exp_f32_e32 v34, v34
	v_pk_mul_f32 v[52:53], v[20:21], v[0:1] op_sel_hi:[1,0]
	v_pk_mul_f32 v[54:55], v[18:19], v[0:1] op_sel_hi:[1,0]
	s_waitcnt lgkmcnt(1)
	v_pk_fma_f32 v[46:47], v[46:47], v[34:35], v[52:53] op_sel_hi:[1,0,1]
	v_pk_fma_f32 v[44:45], v[44:45], v[34:35], v[54:55] op_sel_hi:[1,0,1]
	v_pk_mul_f32 v[56:57], v[24:25], v[0:1] op_sel_hi:[1,0]
	v_pk_mul_f32 v[58:59], v[22:23], v[0:1] op_sel_hi:[1,0]
	ds_read_b128 v[52:55], v41 offset:128
	s_waitcnt lgkmcnt(1)
	v_pk_fma_f32 v[50:51], v[50:51], v[34:35], v[56:57] op_sel_hi:[1,0,1]
	v_pk_fma_f32 v[48:49], v[48:49], v[34:35], v[58:59] op_sel_hi:[1,0,1]
	ds_read_b128 v[56:59], v41 offset:192
	s_waitcnt lgkmcnt(0)
	v_pk_mul_f32 v[60:61], v[28:29], v[0:1] op_sel_hi:[1,0]
	v_pk_mul_f32 v[62:63], v[26:27], v[0:1] op_sel_hi:[1,0]
	s_waitcnt lgkmcnt(1)
	v_pk_fma_f32 v[54:55], v[54:55], v[34:35], v[60:61] op_sel_hi:[1,0,1]
	v_pk_fma_f32 v[52:53], v[52:53], v[34:35], v[62:63] op_sel_hi:[1,0,1]
	v_pk_mul_f32 v[60:61], v[32:33], v[0:1] op_sel_hi:[1,0]
	v_pk_mul_f32 v[62:63], v[30:31], v[0:1] op_sel_hi:[1,0]
	s_waitcnt lgkmcnt(0)
	v_pk_fma_f32 v[58:59], v[34:35], v[58:59], v[60:61] op_sel_hi:[0,1,1]
	v_pk_fma_f32 v[56:57], v[34:35], v[56:57], v[62:63] op_sel_hi:[0,1,1]
	ds_write_b128 v41, v[44:47]
	ds_write_b128 v41, v[48:51] offset:64
	ds_write_b128 v41, v[52:55] offset:128
	ds_write_b128 v41, v[56:59] offset:192
	s_and_saveexec_b64 s[48:49], s[46:47]
	v_mul_f32_e32 v37, v135, v0
	v_fmac_f32_e32 v37, v35, v34
	ds_write_b64 v42, v[36:37]
	s_or_b64 exec, exec, s[48:49]
	s_mov_b64 s[48:49], 0
